# v49 + FFN-in K-loop A-fragment ds_read addresses folded into one base VGPR + offset immediates (4 v_add_u32 per iteration dropped)
# speedup vs baseline: 1.0095x; 1.0017x over previous
;     __device__ __forceinline__ void operator()(const f32x4 (&acc)[2][2][4][2], const Unit& u, int wr, int wc, int fr, int fq) const {
;         const int row0 = u.pm * BM + wr * 64 + fr, col0 = u.pn * HALF + wc * 32 + 8 * fq;
;         float rs8[2][4];
;         { f32x4 pa[2][4], pb[2][4];
; #pragma unroll
;           for (int ai = 0; ai < 2; ++ai)
; #pragma unroll
;             for (int m = 0; m < 4; ++m) { const float* p_ = st2 + (size_t)(row0 + ai * HALF + m * 16) * 8; pa[ai][m] = *(const f32x4*)p_; pb[ai][m] = *(const f32x4*)(p_ + 4); }
;           __builtin_amdgcn_sched_barrier(0);
; #pragma unroll
;           for (int ai = 0; ai < 2; ++ai)
; #pragma unroll
;             for (int m = 0; m < 4; ++m) { const f32x4 t_ = pa[ai][m] + pb[ai][m]; rs8[ai][m] = __builtin_amdgcn_rsqf(((t_[0] + t_[1]) + (t_[2] + t_[3])) * (1.0f / (float)D) + 1e-6f); }
;           __builtin_amdgcn_sched_barrier(0); }
.Lmy_rsfill_done:
	s_or_b64 exec, exec, s[100:101]
	s_mov_b32 s100, s54
	s_waitcnt lgkmcnt(0)
	s_barrier
	v_readlane_b32 s19, v253, 54
	s_branch .LBB0_134
	s_nop 0
	s_nop 0
	s_nop 0
	s_nop 0
	s_nop 0
	s_nop 0
	s_nop 0
	s_nop 0
	s_nop 0
	s_nop 0
	s_nop 0
	s_nop 0
	s_nop 0
	s_nop 0
	s_nop 0
	s_nop 0
	s_nop 0
	s_nop 0
	s_nop 0
	s_nop 0
	s_nop 0
	s_nop 0
	s_nop 0
	s_nop 0
	s_nop 0
	s_nop 0
	s_nop 0
	s_nop 0
	s_nop 0
	s_nop 0
.LBB0_132:
	s_mov_b64 s[26:27], 0

; #define PG8_STAGE(bufoff, gbase, voff) do { _Pragma("unroll") for (int _i = 0; _i < 2; ++_i) \
;         __builtin_amdgcn_global_load_lds((const unsigned*)((const char*)(gbase) + (voff)[_i]), (LAS unsigned*)(lds + (bufoff) + ldsw + _i * 8192), 16, 0, 0); } while (0)
; #define PG8_LDA(dst, b, h) do { _Pragma("unroll") for (int m = 0; m < 4; ++m) _Pragma("unroll") for (int k = 0; k < 2; ++k) dst[m][k] = *(const LAS bf16x8*)(lds + PG8_SA(b, h) + aoff + m * 2048 + k * 1024); } while (0)
; #define PG8_LDB(dst, b, h) do { _Pragma("unroll") for (int n = 0; n < 2; ++n) _Pragma("unroll") for (int k = 0; k < 2; ++k) dst[n][k] = *(const LAS bf16x8*)(lds + PG8_SB(b, h) + boff + n * 2048 + k * 1024); } while (0)
; #define PG8_MMA(ai, bj, At, Bt) do { __builtin_amdgcn_s_setprio(1); _Pragma("unroll") for (int m = 0; m < 4; ++m) _Pragma("unroll") for (int n = 0; n < 2; ++n) _Pragma("unroll") for (int k = 0; k < 2; ++k) \
;         acc[ai][bj][m][n] = __builtin_amdgcn_mfma_f32_16x16x32_bf16(Bt[n][k], At[m][k], acc[ai][bj][m][n], 0, 0, 0); __builtin_amdgcn_s_setprio(0); } while (0)
; #define PG8_WAIT_V(n) asm volatile("s_waitcnt vmcnt(" #n ")" ::: "memory")
; #define PG8_WAIT_L(n) asm volatile("s_waitcnt lgkmcnt(" #n ")" ::: "memory")
; #define PG8_BAR __builtin_amdgcn_s_barrier()
; #define PG8_SCHED __builtin_amdgcn_sched_barrier(0)
; template <class Epi, class Sched>
; __device__ __forceinline__ void gemm_phase(LAS unsigned char* lds, const Gemm g, const Sched& S, const Epi& E) {
;     ...
;             PG8_LDB(B0, 0, 0); PG8_LDB(B1, 0, 1); PG8_SCHED; PG8_LDA(At, 0, 0); PG8_STAGE(PG8_SA(1, 1), a1 + hstepA, voffA);
;             PG8_WAIT_V(8); PG8_WAIT_L(0); PG8_BAR; PG8_MMA(0, 0, At, B0); PG8_MMA(0, 1, At, B1); PG8_BAR; PG8_SCHED;
;             PG8_LDA(At, 0, 1); PG8_STAGE(PG8_SB(0, 0), b2, voffB); PG8_STAGE(PG8_SB(0, 1), b2 + hstepB, voffB); PG8_STAGE(PG8_SA(0, 0), a2, voffA);
.LBB0_137:
	s_add_u32 s28, s26, 0xfff80080
	s_addc_u32 s29, s27, -1
	s_add_i32 s60, 0, 0x10000
	s_cmp_eq_u32 s59, 28
	s_cselect_b32 s41, s21, s29
	s_cselect_b32 s40, s55, s28
	s_cselect_b32 s29, s19, s58
	s_cselect_b32 s28, s56, s57
	s_add_i32 s62, 0, 0x14000
	ds_read_b128 v[142:145], v248
	ds_read_b128 v[146:149], v248 offset:1024
	ds_read_b128 v[150:153], v248 offset:2048
	ds_read_b128 v[154:157], v248 offset:3072
	ds_read_b128 v[162:165], v248 offset:16384
	ds_read_b128 v[166:169], v248 offset:17408
	ds_read_b128 v[170:173], v248 offset:18432
	ds_read_b128 v[174:177], v248 offset:19456
	s_add_i32 m0, s46, 0xc000
	ds_read_b128 v[178:181], v161
	ds_read_b128 v[182:185], v161 offset:1024
	ds_read_b128 v[186:189], v161 offset:2048
	ds_read_b128 v[190:193], v161 offset:3072
	ds_read_b128 v[194:197], v161 offset:4096
	ds_read_b128 v[212:215], v161 offset:5120
	ds_read_b128 v[216:219], v161 offset:6144
	ds_read_b128 v[220:223], v161 offset:7168
	global_load_lds_dwordx4 v138, s[26:27]
	s_add_i32 m0, s46, 0xe000
	s_nop 0
	global_load_lds_dwordx4 v140, s[26:27]
	s_waitcnt vmcnt(8)
	s_waitcnt lgkmcnt(0)
	s_barrier
	s_waitcnt lgkmcnt(0)
	v_mfma_f32_16x16x32_bf16 v[130:133], v[142:145], v[178:181], v[130:133]
	v_mfma_f32_16x16x32_bf16 v[122:125], v[150:153], v[178:181], v[122:125]
	v_mfma_f32_16x16x32_bf16 v[114:117], v[142:145], v[186:189], v[114:117]
	v_mfma_f32_16x16x32_bf16 v[106:109], v[150:153], v[186:189], v[106:109]
	v_mfma_f32_16x16x32_bf16 v[98:101], v[142:145], v[194:197], v[98:101]
	v_mfma_f32_16x16x32_bf16 v[90:93], v[150:153], v[194:197], v[90:93]
	v_mfma_f32_16x16x32_bf16 v[82:85], v[142:145], v[216:219], v[82:85]
	v_mfma_f32_16x16x32_bf16 v[74:77], v[150:153], v[216:219], v[74:77]
	v_mfma_f32_16x16x32_bf16 v[130:133], v[146:149], v[182:185], v[130:133]
	v_mfma_f32_16x16x32_bf16 v[122:125], v[154:157], v[182:185], v[122:125]
	v_mfma_f32_16x16x32_bf16 v[114:117], v[146:149], v[190:193], v[114:117]
	v_mfma_f32_16x16x32_bf16 v[106:109], v[154:157], v[190:193], v[106:109]
	v_mfma_f32_16x16x32_bf16 v[98:101], v[146:149], v[212:215], v[98:101]
	v_mfma_f32_16x16x32_bf16 v[90:93], v[154:157], v[212:215], v[90:93]
	v_mfma_f32_16x16x32_bf16 v[82:85], v[146:149], v[220:223], v[82:85]
	v_mfma_f32_16x16x32_bf16 v[74:77], v[154:157], v[220:223], v[74:77]
	v_mfma_f32_16x16x32_bf16 v[126:129], v[162:165], v[178:181], v[126:129]
	v_mfma_f32_16x16x32_bf16 v[118:121], v[170:173], v[178:181], v[118:121]
	v_mfma_f32_16x16x32_bf16 v[110:113], v[162:165], v[186:189], v[110:113]
	v_mfma_f32_16x16x32_bf16 v[102:105], v[170:173], v[186:189], v[102:105]
	v_mfma_f32_16x16x32_bf16 v[94:97], v[162:165], v[194:197], v[94:97]
	v_mfma_f32_16x16x32_bf16 v[86:89], v[170:173], v[194:197], v[86:89]
	v_mfma_f32_16x16x32_bf16 v[78:81], v[162:165], v[216:219], v[78:81]
	v_mfma_f32_16x16x32_bf16 v[70:73], v[170:173], v[216:219], v[70:73]
	v_mfma_f32_16x16x32_bf16 v[126:129], v[166:169], v[182:185], v[126:129]
	v_mfma_f32_16x16x32_bf16 v[118:121], v[174:177], v[182:185], v[118:121]
	v_mfma_f32_16x16x32_bf16 v[110:113], v[166:169], v[190:193], v[110:113]
	v_mfma_f32_16x16x32_bf16 v[102:105], v[174:177], v[190:193], v[102:105]
	v_mfma_f32_16x16x32_bf16 v[94:97], v[166:169], v[212:215], v[94:97]
	v_mfma_f32_16x16x32_bf16 v[86:89], v[174:177], v[212:215], v[86:89]
	v_mfma_f32_16x16x32_bf16 v[78:81], v[166:169], v[220:223], v[78:81]
	v_mfma_f32_16x16x32_bf16 v[70:73], v[174:177], v[220:223], v[70:73]
	s_barrier
	s_add_i32 s60, s60, s45
	v_lshl_add_u64 v[224:225], s[28:29], 0, v[4:5]
	s_mov_b32 m0, s60
	ds_read_b128 v[178:181], v161 offset:16384
	ds_read_b128 v[182:185], v161 offset:17408
	ds_read_b128 v[186:189], v161 offset:18432
	ds_read_b128 v[190:193], v161 offset:19456
	ds_read_b128 v[194:197], v161 offset:20480
	ds_read_b128 v[212:215], v161 offset:21504
	ds_read_b128 v[216:219], v161 offset:22528
	ds_read_b128 v[220:223], v161 offset:23552
	global_load_lds_dwordx4 v[224:225], off
	s_add_i32 m0, s60, 0x2000
	s_add_u32 s60, s28, 0x80000
	v_lshl_add_u64 v[226:227], s[28:29], 0, v[2:3]
	s_addc_u32 s61, s29, 0
	s_add_i32 s62, s62, s45
	global_load_lds_dwordx4 v[226:227], off
	s_mov_b32 m0, s62
	v_lshl_add_u64 v[230:231], s[40:41], 0, v[134:135]
	global_load_lds_dwordx4 v4, s[60:61]
	s_add_i32 m0, s62, 0x2000
	s_nop 0
	global_load_lds_dwordx4 v2, s[60:61]
	v_lshl_add_u64 v[228:229], s[40:41], 0, v[136:137]
	s_mov_b32 m0, s46
	s_nop 0
	global_load_lds_dwordx4 v[228:229], off
	s_mov_b32 m0, s47
	s_nop 0
	global_load_lds_dwordx4 v[230:231], off
	s_waitcnt vmcnt(8)
	s_waitcnt lgkmcnt(0)
	s_barrier
; #define PG8_STAGE(bufoff, gbase, voff) do { _Pragma("unroll") for (int _i = 0; _i < 2; ++_i) \
;         __builtin_amdgcn_global_load_lds((const unsigned*)((const char*)(gbase) + (voff)[_i]), (LAS unsigned*)(lds + (bufoff) + ldsw + _i * 8192), 16, 0, 0); } while (0)
; #define PG8_LDA(dst, b, h) do { _Pragma("unroll") for (int m = 0; m < 4; ++m) _Pragma("unroll") for (int k = 0; k < 2; ++k) dst[m][k] = *(const LAS bf16x8*)(lds + PG8_SA(b, h) + aoff + m * 2048 + k * 1024); } while (0)
; #define PG8_LDB(dst, b, h) do { _Pragma("unroll") for (int n = 0; n < 2; ++n) _Pragma("unroll") for (int k = 0; k < 2; ++k) dst[n][k] = *(const LAS bf16x8*)(lds + PG8_SB(b, h) + boff + n * 2048 + k * 1024); } while (0)
; #define PG8_MMA(ai, bj, At, Bt) do { __builtin_amdgcn_s_setprio(1); _Pragma("unroll") for (int m = 0; m < 4; ++m) _Pragma("unroll") for (int n = 0; n < 2; ++n) _Pragma("unroll") for (int k = 0; k < 2; ++k) \
;         acc[ai][bj][m][n] = __builtin_amdgcn_mfma_f32_16x16x32_bf16(Bt[n][k], At[m][k], acc[ai][bj][m][n], 0, 0, 0); __builtin_amdgcn_s_setprio(0); } while (0)
; #define PG8_WAIT_V(n) asm volatile("s_waitcnt vmcnt(" #n ")" ::: "memory")
; #define PG8_WAIT_L(n) asm volatile("s_waitcnt lgkmcnt(" #n ")" ::: "memory")
; #define PG8_BAR __builtin_amdgcn_s_barrier()
; #define PG8_SCHED __builtin_amdgcn_sched_barrier(0)
; template <class Epi, class Sched>
; __device__ __forceinline__ void gemm_phase(LAS unsigned char* lds, const Gemm g, const Sched& S, const Epi& E) {
;     ...
;             PG8_LDB(B0, 0, 0); PG8_LDB(B1, 0, 1); PG8_SCHED; PG8_LDA(At, 0, 0); PG8_STAGE(PG8_SA(1, 1), a1 + hstepA, voffA);
;             PG8_WAIT_V(8); PG8_WAIT_L(0); PG8_BAR; PG8_MMA(0, 0, At, B0); PG8_MMA(0, 1, At, B1); PG8_BAR; PG8_SCHED;
;             PG8_LDA(At, 0, 1); PG8_STAGE(PG8_SB(0, 0), b2, voffB); PG8_STAGE(PG8_SB(0, 1), b2 + hstepB, voffB); PG8_STAGE(PG8_SA(0, 0), a2, voffA);
;             PG8_WAIT_V(8); PG8_WAIT_L(0); PG8_BAR; PG8_MMA(1, 0, At, B0); PG8_MMA(1, 1, At, B1); PG8_BAR; PG8_SCHED;
;             PG8_LDB(B0, 1, 0); PG8_LDB(B1, 1, 1); PG8_SCHED; PG8_LDA(At, 1, 0); PG8_STAGE(PG8_SA(0, 1), a2 + hstepA, voffA);
;             PG8_WAIT_V(8); PG8_WAIT_L(0); PG8_BAR; PG8_MMA(0, 0, At, B0); PG8_MMA(0, 1, At, B1); PG8_BAR; PG8_SCHED;
	s_waitcnt lgkmcnt(0)
	v_mfma_f32_16x16x32_bf16 v[66:69], v[142:145], v[178:181], v[66:69]
	v_mfma_f32_16x16x32_bf16 v[58:61], v[150:153], v[178:181], v[58:61]
	v_mfma_f32_16x16x32_bf16 v[50:53], v[142:145], v[186:189], v[50:53]
	v_mfma_f32_16x16x32_bf16 v[42:45], v[150:153], v[186:189], v[42:45]
	v_mfma_f32_16x16x32_bf16 v[34:37], v[142:145], v[194:197], v[34:37]
	v_mfma_f32_16x16x32_bf16 v[26:29], v[150:153], v[194:197], v[26:29]
	v_mfma_f32_16x16x32_bf16 v[18:21], v[142:145], v[216:219], v[18:21]
	v_mfma_f32_16x16x32_bf16 v[10:13], v[150:153], v[216:219], v[10:13]
	v_mfma_f32_16x16x32_bf16 v[66:69], v[146:149], v[182:185], v[66:69]
	v_mfma_f32_16x16x32_bf16 v[58:61], v[154:157], v[182:185], v[58:61]
	v_mfma_f32_16x16x32_bf16 v[50:53], v[146:149], v[190:193], v[50:53]
	v_mfma_f32_16x16x32_bf16 v[42:45], v[154:157], v[190:193], v[42:45]
	v_mfma_f32_16x16x32_bf16 v[34:37], v[146:149], v[212:215], v[34:37]
	v_mfma_f32_16x16x32_bf16 v[26:29], v[154:157], v[212:215], v[26:29]
	v_mfma_f32_16x16x32_bf16 v[18:21], v[146:149], v[220:223], v[18:21]
	v_mfma_f32_16x16x32_bf16 v[10:13], v[154:157], v[220:223], v[10:13]
	v_mfma_f32_16x16x32_bf16 v[62:65], v[162:165], v[178:181], v[62:65]
	v_mfma_f32_16x16x32_bf16 v[54:57], v[170:173], v[178:181], v[54:57]
	v_mfma_f32_16x16x32_bf16 v[46:49], v[162:165], v[186:189], v[46:49]
	v_mfma_f32_16x16x32_bf16 v[38:41], v[170:173], v[186:189], v[38:41]
	v_mfma_f32_16x16x32_bf16 v[30:33], v[162:165], v[194:197], v[30:33]
	v_mfma_f32_16x16x32_bf16 v[22:25], v[170:173], v[194:197], v[22:25]
	v_mfma_f32_16x16x32_bf16 v[14:17], v[162:165], v[216:219], v[14:17]
	v_mfma_f32_16x16x32_bf16 v[6:9], v[170:173], v[216:219], v[6:9]
	v_mfma_f32_16x16x32_bf16 v[62:65], v[166:169], v[182:185], v[62:65]
	v_mfma_f32_16x16x32_bf16 v[54:57], v[174:177], v[182:185], v[54:57]
	v_mfma_f32_16x16x32_bf16 v[46:49], v[166:169], v[190:193], v[46:49]
	v_mfma_f32_16x16x32_bf16 v[38:41], v[174:177], v[190:193], v[38:41]
	v_mfma_f32_16x16x32_bf16 v[30:33], v[166:169], v[212:215], v[30:33]
	v_mfma_f32_16x16x32_bf16 v[22:25], v[174:177], v[212:215], v[22:25]
	v_mfma_f32_16x16x32_bf16 v[14:17], v[166:169], v[220:223], v[14:17]
	v_mfma_f32_16x16x32_bf16 v[6:9], v[174:177], v[220:223], v[6:9]
	s_barrier
	s_add_i32 s60, 0, 0x18000
	s_add_i32 s61, 0, 0x1c000
	ds_read_b128 v[142:145], v248 offset:32768
	ds_read_b128 v[146:149], v248 offset:33792
	ds_read_b128 v[150:153], v248 offset:34816
	ds_read_b128 v[154:157], v248 offset:35840
	ds_read_b128 v[162:165], v248 offset:49152
	ds_read_b128 v[166:169], v248 offset:50176
	ds_read_b128 v[170:173], v248 offset:51200
	ds_read_b128 v[174:177], v248 offset:52224
	s_add_u32 s40, s40, 0x80000
	s_addc_u32 s41, s41, 0
	s_mov_b32 m0, s48
	ds_read_b128 v[178:181], v161 offset:32768
	ds_read_b128 v[182:185], v161 offset:33792
	ds_read_b128 v[186:189], v161 offset:34816
	ds_read_b128 v[190:193], v161 offset:35840
	ds_read_b128 v[194:197], v161 offset:36864
	ds_read_b128 v[212:215], v161 offset:37888
	ds_read_b128 v[216:219], v161 offset:38912
	ds_read_b128 v[220:223], v161 offset:39936
	global_load_lds_dwordx4 v136, s[40:41]
	s_mov_b32 m0, s49
	s_nop 0
	global_load_lds_dwordx4 v134, s[40:41]
	s_waitcnt vmcnt(8)
	s_waitcnt lgkmcnt(0)
	s_barrier
	s_waitcnt lgkmcnt(0)
	v_mfma_f32_16x16x32_bf16 v[130:133], v[142:145], v[178:181], v[130:133]
	v_mfma_f32_16x16x32_bf16 v[122:125], v[150:153], v[178:181], v[122:125]
	v_mfma_f32_16x16x32_bf16 v[114:117], v[142:145], v[186:189], v[114:117]
	v_mfma_f32_16x16x32_bf16 v[106:109], v[150:153], v[186:189], v[106:109]
	v_mfma_f32_16x16x32_bf16 v[98:101], v[142:145], v[194:197], v[98:101]
	v_mfma_f32_16x16x32_bf16 v[90:93], v[150:153], v[194:197], v[90:93]
	v_mfma_f32_16x16x32_bf16 v[82:85], v[142:145], v[216:219], v[82:85]
	v_mfma_f32_16x16x32_bf16 v[74:77], v[150:153], v[216:219], v[74:77]
	v_mfma_f32_16x16x32_bf16 v[130:133], v[146:149], v[182:185], v[130:133]
	v_mfma_f32_16x16x32_bf16 v[122:125], v[154:157], v[182:185], v[122:125]
	v_mfma_f32_16x16x32_bf16 v[114:117], v[146:149], v[190:193], v[114:117]
	v_mfma_f32_16x16x32_bf16 v[106:109], v[154:157], v[190:193], v[106:109]
	v_mfma_f32_16x16x32_bf16 v[98:101], v[146:149], v[212:215], v[98:101]
	v_mfma_f32_16x16x32_bf16 v[90:93], v[154:157], v[212:215], v[90:93]
	v_mfma_f32_16x16x32_bf16 v[82:85], v[146:149], v[220:223], v[82:85]
	v_mfma_f32_16x16x32_bf16 v[74:77], v[154:157], v[220:223], v[74:77]
	v_mfma_f32_16x16x32_bf16 v[126:129], v[162:165], v[178:181], v[126:129]
	v_mfma_f32_16x16x32_bf16 v[118:121], v[170:173], v[178:181], v[118:121]
	v_mfma_f32_16x16x32_bf16 v[110:113], v[162:165], v[186:189], v[110:113]
	v_mfma_f32_16x16x32_bf16 v[102:105], v[170:173], v[186:189], v[102:105]
	v_mfma_f32_16x16x32_bf16 v[94:97], v[162:165], v[194:197], v[94:97]
	v_mfma_f32_16x16x32_bf16 v[86:89], v[170:173], v[194:197], v[86:89]
	v_mfma_f32_16x16x32_bf16 v[78:81], v[162:165], v[216:219], v[78:81]
	v_mfma_f32_16x16x32_bf16 v[70:73], v[170:173], v[216:219], v[70:73]
	v_mfma_f32_16x16x32_bf16 v[126:129], v[166:169], v[182:185], v[126:129]
	v_mfma_f32_16x16x32_bf16 v[118:121], v[174:177], v[182:185], v[118:121]
	v_mfma_f32_16x16x32_bf16 v[110:113], v[166:169], v[190:193], v[110:113]
	v_mfma_f32_16x16x32_bf16 v[102:105], v[174:177], v[190:193], v[102:105]
	v_mfma_f32_16x16x32_bf16 v[94:97], v[166:169], v[212:215], v[94:97]
	v_mfma_f32_16x16x32_bf16 v[86:89], v[174:177], v[212:215], v[86:89]
	v_mfma_f32_16x16x32_bf16 v[78:81], v[166:169], v[220:223], v[78:81]
	v_mfma_f32_16x16x32_bf16 v[70:73], v[174:177], v[220:223], v[70:73]
	s_barrier
; #define PG8_STAGE(bufoff, gbase, voff) do { _Pragma("unroll") for (int _i = 0; _i < 2; ++_i) \
;         __builtin_amdgcn_global_load_lds((const unsigned*)((const char*)(gbase) + (voff)[_i]), (LAS unsigned*)(lds + (bufoff) + ldsw + _i * 8192), 16, 0, 0); } while (0)
; #define PG8_LDA(dst, b, h) do { _Pragma("unroll") for (int m = 0; m < 4; ++m) _Pragma("unroll") for (int k = 0; k < 2; ++k) dst[m][k] = *(const LAS bf16x8*)(lds + PG8_SA(b, h) + aoff + m * 2048 + k * 1024); } while (0)
; #define PG8_MMA(ai, bj, At, Bt) do { __builtin_amdgcn_s_setprio(1); _Pragma("unroll") for (int m = 0; m < 4; ++m) _Pragma("unroll") for (int n = 0; n < 2; ++n) _Pragma("unroll") for (int k = 0; k < 2; ++k) \
;         acc[ai][bj][m][n] = __builtin_amdgcn_mfma_f32_16x16x32_bf16(Bt[n][k], At[m][k], acc[ai][bj][m][n], 0, 0, 0); __builtin_amdgcn_s_setprio(0); } while (0)
; #define PG8_WAIT_V(n) asm volatile("s_waitcnt vmcnt(" #n ")" ::: "memory")
; #define PG8_WAIT_L(n) asm volatile("s_waitcnt lgkmcnt(" #n ")" ::: "memory")
; #define PG8_BAR __builtin_amdgcn_s_barrier()
; #define PG8_SCHED __builtin_amdgcn_sched_barrier(0)
; template <class Epi, class Sched>
; __device__ __forceinline__ void gemm_phase(LAS unsigned char* lds, const Gemm g, const Sched& S, const Epi& E) {
;     ...
;             PG8_LDA(At, 1, 1); PG8_STAGE(PG8_SB(1, 0), b3, voffB); PG8_STAGE(PG8_SB(1, 1), b3 + hstepB, voffB); PG8_STAGE(PG8_SA(1, 0), a3, voffA);
;             PG8_WAIT_V(8); PG8_WAIT_L(0); PG8_BAR; PG8_MMA(1, 0, At, B0); PG8_MMA(1, 1, At, B1); PG8_BAR; PG8_SCHED;
;         }
;         if (wr == 0) PG8_BAR;
	s_add_i32 s40, s60, s45
	s_add_i32 m0, s40, 0xffffff80
	ds_read_b128 v[178:181], v161 offset:49152
	ds_read_b128 v[182:185], v161 offset:50176
	ds_read_b128 v[186:189], v161 offset:51200
	ds_read_b128 v[190:193], v161 offset:52224
	ds_read_b128 v[194:197], v161 offset:53248
	ds_read_b128 v[212:215], v161 offset:54272
	ds_read_b128 v[216:219], v161 offset:55296
	ds_read_b128 v[220:223], v161 offset:56320
	global_load_lds_dwordx4 v[224:225], off offset:128
	s_add_i32 m0, s40, 0x1f80
	s_add_u32 s28, s28, 0x80080
	s_addc_u32 s29, s29, 0
	s_add_i32 s40, s61, s45
	global_load_lds_dwordx4 v[226:227], off offset:128
	s_mov_b32 m0, s40
	s_nop 0
	global_load_lds_dwordx4 v4, s[28:29]
	s_add_i32 m0, s40, 0x2000
	s_nop 0
	global_load_lds_dwordx4 v2, s[28:29]
	s_add_i32 m0, s50, 0xffffff80
	s_nop 0
	global_load_lds_dwordx4 v[228:229], off offset:128
	s_add_i32 m0, s51, 0xffffff80
	s_nop 0
	global_load_lds_dwordx4 v[230:231], off offset:128
	s_waitcnt vmcnt(8)
	s_waitcnt lgkmcnt(0)
	s_barrier
	s_waitcnt lgkmcnt(0)
	v_mfma_f32_16x16x32_bf16 v[66:69], v[142:145], v[178:181], v[66:69]
	v_mfma_f32_16x16x32_bf16 v[58:61], v[150:153], v[178:181], v[58:61]
	v_mfma_f32_16x16x32_bf16 v[50:53], v[142:145], v[186:189], v[50:53]
	v_mfma_f32_16x16x32_bf16 v[42:45], v[150:153], v[186:189], v[42:45]
	v_mfma_f32_16x16x32_bf16 v[34:37], v[142:145], v[194:197], v[34:37]
	v_mfma_f32_16x16x32_bf16 v[26:29], v[150:153], v[194:197], v[26:29]
	v_mfma_f32_16x16x32_bf16 v[18:21], v[142:145], v[216:219], v[18:21]
	v_mfma_f32_16x16x32_bf16 v[10:13], v[150:153], v[216:219], v[10:13]
	v_mfma_f32_16x16x32_bf16 v[66:69], v[146:149], v[182:185], v[66:69]
	v_mfma_f32_16x16x32_bf16 v[58:61], v[154:157], v[182:185], v[58:61]
	v_mfma_f32_16x16x32_bf16 v[50:53], v[146:149], v[190:193], v[50:53]
	v_mfma_f32_16x16x32_bf16 v[42:45], v[154:157], v[190:193], v[42:45]
	v_mfma_f32_16x16x32_bf16 v[34:37], v[146:149], v[212:215], v[34:37]
	v_mfma_f32_16x16x32_bf16 v[26:29], v[154:157], v[212:215], v[26:29]
	v_mfma_f32_16x16x32_bf16 v[18:21], v[146:149], v[220:223], v[18:21]
	v_mfma_f32_16x16x32_bf16 v[10:13], v[154:157], v[220:223], v[10:13]
	v_mfma_f32_16x16x32_bf16 v[62:65], v[162:165], v[178:181], v[62:65]
	v_mfma_f32_16x16x32_bf16 v[54:57], v[170:173], v[178:181], v[54:57]
	v_mfma_f32_16x16x32_bf16 v[46:49], v[162:165], v[186:189], v[46:49]
	v_mfma_f32_16x16x32_bf16 v[38:41], v[170:173], v[186:189], v[38:41]
	v_mfma_f32_16x16x32_bf16 v[30:33], v[162:165], v[194:197], v[30:33]
	v_mfma_f32_16x16x32_bf16 v[22:25], v[170:173], v[194:197], v[22:25]
	v_mfma_f32_16x16x32_bf16 v[14:17], v[162:165], v[216:219], v[14:17]
	v_mfma_f32_16x16x32_bf16 v[6:9], v[170:173], v[216:219], v[6:9]
	v_mfma_f32_16x16x32_bf16 v[62:65], v[166:169], v[182:185], v[62:65]
	v_mfma_f32_16x16x32_bf16 v[54:57], v[174:177], v[182:185], v[54:57]
	v_mfma_f32_16x16x32_bf16 v[46:49], v[166:169], v[190:193], v[46:49]
	v_mfma_f32_16x16x32_bf16 v[38:41], v[174:177], v[190:193], v[38:41]
	v_mfma_f32_16x16x32_bf16 v[30:33], v[166:169], v[212:215], v[30:33]
	v_mfma_f32_16x16x32_bf16 v[22:25], v[174:177], v[212:215], v[22:25]
	v_mfma_f32_16x16x32_bf16 v[14:17], v[166:169], v[220:223], v[14:17]
	v_mfma_f32_16x16x32_bf16 v[6:9], v[174:177], v[220:223], v[6:9]
	s_barrier
	s_add_i32 s59, s59, 2
	s_add_u32 s26, s26, 0x100
	s_addc_u32 s27, s27, 0
	s_add_u32 s57, s57, 0x100
	s_addc_u32 s58, s58, 0
	s_cmp_gt_u32 s59, 29
	s_cbranch_scc0 .LBB0_137
	s_and_b64 vcc, exec, s[16:17]
	s_cbranch_vccz .LBB0_140
	s_barrier

; #define PG8_STAGE(bufoff, gbase, voff) do { _Pragma("unroll") for (int _i = 0; _i < 2; ++_i) \
;         __builtin_amdgcn_global_load_lds((const unsigned*)((const char*)(gbase) + (voff)[_i]), (LAS unsigned*)(lds + (bufoff) + ldsw + _i * 8192), 16, 0, 0); } while (0)
; #define PG8_WAIT_V(n) asm volatile("s_waitcnt vmcnt(" #n ")" ::: "memory")
; #define PG8_BAR __builtin_amdgcn_s_barrier()
; template <class Epi, class Sched>
; __device__ __forceinline__ void gemm_phase(LAS unsigned char* lds, const Gemm g, const Sched& S, const Epi& E) {
;     ...
;     for (int i = 0; i < 2; ++i) { int R, C; stage_rc(tid * 16 + i * 8192, R, C); const int Rb = Epi::PERM ? ((R & ~31) + perm32(R & 31)) : R;
;         voffA[i] = (unsigned)(R * g.lda + C) * 2u; voffB[i] = (unsigned)(Rb * g.ldb + C) * 2u; }
;     const size_t kstep = (size_t)(BK * 2);
;     const size_t hstepA = (size_t)HALF * g.lda * 2, hstepB = (size_t)HALF * g.ldb * 2;
;     const size_t tstepA = 2 * hstepA, tstepB = 2 * hstepB;
;     const unsigned ldsw = (unsigned)wid * 1024u;
;     const int aoff = lds_byte(wr * 64 + fr, fq * 8), boff = lds_byte(wc * 32 + fr, fq * 8);
;     ...
;     Unit cur, nxt; int ui = 0;
;     if (!S.next(0, cur)) return;
;     f32x4 acc[2][2][4][2];
; #pragma unroll
;     for (int a = 0; a < 2; ++a)
; #pragma unroll
;         for (int b = 0; b < 2; ++b)
; #pragma unroll
;             for (int m = 0; m < 4; ++m)
; #pragma unroll
;                 for (int n = 0; n < 2; ++n) acc[a][b][m][n] = (f32x4){0.f, 0.f, 0.f, 0.f};
;     bf16x8 At[4][2], B0[2][2], B1[2][2];
;     const char* cA = (const char*)g.A + (size_t)cur.pm * tstepA + (size_t)cur.ka * 2; const char* cB = (const char*)g.Bt + (size_t)cur.pn * tstepB;
;     S.a_ready(cur);
;     PG8_STAGE(PG8_SB(0, 0), cB, voffB); PG8_STAGE(PG8_SB(0, 1), cB + hstepB, voffB); PG8_STAGE(PG8_SA(0, 0), cA, voffA); PG8_STAGE(PG8_SA(0, 1), cA + hstepA, voffA);
;     if (wr == 1) PG8_BAR;
;     PG8_WAIT_V(2); PG8_BAR;
;     PG8_STAGE(PG8_SB(1, 0), cB + kstep, voffB); PG8_STAGE(PG8_SA(1, 0), cA + kstep, voffA); PG8_STAGE(PG8_SB(1, 1), cB + hstepB + kstep, voffB);
;     PG8_WAIT_V(6); PG8_BAR;
.LBB0_267:
	v_lshl_add_u64 v[14:15], s[24:25], 0, v[4:5]
	v_mov_b32_e32 v3, v5
	v_and_b32_e32 v142, 15, v143
	v_and_b32_e32 v22, 48, v143
	v_lshlrev_b32_e32 v23, 2, v143
	v_lshl_add_u64 v[16:17], s[24:25], 0, v[2:3]
	s_and_b32 s48, s44, 3
	v_lshl_or_b32 v22, v142, 6, v22
	s_lshl_b32 s4, s47, 13
	v_and_b32_e32 v23, 32, v23
	s_add_i32 m0, s50, 0x18000
	v_lshl_add_u64 v[14:15], v[14:15], 0, s[36:37]
	v_lshl_add_u64 v[18:19], s[20:21], 0, v[4:5]
	v_bitop3_b32 v24, v22, s4, v23 bitop3:0xde
	s_lshl_b32 s4, s48, 12
	s_waitcnt vmcnt(2)
	s_barrier
	global_load_lds_dwordx4 v[14:15], off
	v_lshl_add_u64 v[14:15], v[16:17], 0, s[36:37]
	s_add_i32 m0, s50, 0x1a000
	s_add_i32 s54, s50, 0x8000
	s_add_i32 s55, s50, 0xa000
	v_lshl_add_u64 v[20:21], s[20:21], 0, v[2:3]
	v_bitop3_b32 v144, v22, s4, v23 bitop3:0xde
	global_load_lds_dwordx4 v[14:15], off
	v_lshl_add_u64 v[14:15], v[18:19], 0, s[36:37]
	s_mov_b32 m0, s54
	s_add_u32 s4, s24, 0x158080
	global_load_lds_dwordx4 v[14:15], off
	v_lshl_add_u64 v[14:15], v[20:21], 0, s[36:37]
	s_mov_b32 m0, s55
	s_addc_u32 s5, s25, 0
	global_load_lds_dwordx4 v[14:15], off
	s_add_i32 m0, s50, 0x1c000
	v_lshl_add_u64 v[14:15], s[4:5], 0, v[4:5]
	global_load_lds_dwordx4 v[14:15], off
	v_lshl_add_u64 v[14:15], s[4:5], 0, v[2:3]
	s_add_i32 m0, s50, 0x1e000
	s_movk_i32 s10, 0x1580
	global_load_lds_dwordx4 v[14:15], off
	v_lshrrev_b32_e32 v11, 1, v11
	v_mul_lo_u32 v10, v10, s10
	s_mov_b32 s22, 0x15800
	v_mad_u64_u32 v[10:11], s[4:5], v11, s22, v[10:11]
	v_or_b32_e32 v10, v10, v12
	v_add_lshl_u32 v134, v10, v13, 1
	v_lshrrev_b32_e32 v10, 1, v6
	v_mul_lo_u32 v6, v7, s10
	v_mad_u64_u32 v[6:7], s[4:5], v10, s22, v[6:7]
	s_waitcnt vmcnt(6)
	v_or_b32_e32 v6, v6, v8
	s_cmpk_lt_u32 s45, 0x100
	v_add_lshl_u32 v136, v6, v9, 1
	v_mov_b32_e32 v6, 0
	v_readlane_b32 s4, v254, 13
	s_cselect_b64 s[18:19], -1, 0
	v_mov_b32_e32 v135, v5
	v_mov_b32_e32 v137, v5
	s_mov_b32 s59, 0
	v_add_u32_e32 v145, 0, v24
	s_mov_b32 s10, s4
	v_readlane_b32 s46, v253, 61
	v_mov_b32_e32 v7, v6
	v_mov_b32_e32 v8, v6
	v_mov_b32_e32 v9, v6
	v_mov_b32_e32 v10, v6
	v_mov_b32_e32 v11, v6
	v_mov_b32_e32 v12, v6
	v_mov_b32_e32 v13, v6
	v_mov_b32_e32 v14, v6
	v_mov_b32_e32 v15, v6
	v_mov_b32_e32 v16, v6
	v_mov_b32_e32 v17, v6
	v_mov_b32_e32 v18, v6
	v_mov_b32_e32 v19, v6
	v_mov_b32_e32 v20, v6
	v_mov_b32_e32 v21, v6
	v_mov_b32_e32 v22, v6
	v_mov_b32_e32 v23, v6
	v_mov_b32_e32 v24, v6
	v_mov_b32_e32 v25, v6
	v_mov_b32_e32 v30, v6
	v_mov_b32_e32 v31, v6
	v_mov_b32_e32 v32, v6
	v_mov_b32_e32 v33, v6
	v_mov_b32_e32 v38, v6
	v_mov_b32_e32 v39, v6
	v_mov_b32_e32 v40, v6
	v_mov_b32_e32 v41, v6
	v_mov_b32_e32 v46, v6
	v_mov_b32_e32 v47, v6
	v_mov_b32_e32 v48, v6
	v_mov_b32_e32 v49, v6
	v_mov_b32_e32 v26, v6
	v_mov_b32_e32 v27, v6
	v_mov_b32_e32 v28, v6
	v_mov_b32_e32 v29, v6
	v_mov_b32_e32 v34, v6
	v_mov_b32_e32 v35, v6
	v_mov_b32_e32 v36, v6
	v_mov_b32_e32 v37, v6
	v_mov_b32_e32 v42, v6
	v_mov_b32_e32 v43, v6
	v_mov_b32_e32 v44, v6
	v_mov_b32_e32 v45, v6
	v_mov_b32_e32 v50, v6
	v_mov_b32_e32 v51, v6
	v_mov_b32_e32 v52, v6
	v_mov_b32_e32 v53, v6
	v_mov_b32_e32 v54, v6
	v_mov_b32_e32 v55, v6
	v_mov_b32_e32 v56, v6
	v_mov_b32_e32 v57, v6
	v_mov_b32_e32 v58, v6
	v_mov_b32_e32 v59, v6
	v_mov_b32_e32 v60, v6
	v_mov_b32_e32 v61, v6
	v_mov_b32_e32 v62, v6
	v_mov_b32_e32 v63, v6
	v_mov_b32_e32 v64, v6
	v_mov_b32_e32 v65, v6
	v_mov_b32_e32 v66, v6
	v_mov_b32_e32 v67, v6
	v_mov_b32_e32 v68, v6
	v_mov_b32_e32 v69, v6
	v_mov_b32_e32 v70, v6
	v_mov_b32_e32 v71, v6
	v_mov_b32_e32 v72, v6
	v_mov_b32_e32 v73, v6
	v_mov_b32_e32 v74, v6
	v_mov_b32_e32 v75, v6
	v_mov_b32_e32 v76, v6
	v_mov_b32_e32 v77, v6
	v_mov_b32_e32 v78, v6
	v_mov_b32_e32 v79, v6
	v_mov_b32_e32 v80, v6
	v_mov_b32_e32 v81, v6
	v_mov_b32_e32 v82, v6
	v_mov_b32_e32 v83, v6
	v_mov_b32_e32 v84, v6
	v_mov_b32_e32 v85, v6
	v_mov_b32_e32 v86, v6
	v_mov_b32_e32 v87, v6
	v_mov_b32_e32 v88, v6
	v_mov_b32_e32 v89, v6
	v_mov_b32_e32 v94, v6
	v_mov_b32_e32 v95, v6
	v_mov_b32_e32 v96, v6
	v_mov_b32_e32 v97, v6
	v_mov_b32_e32 v102, v6
	v_mov_b32_e32 v103, v6
	v_mov_b32_e32 v104, v6
	v_mov_b32_e32 v105, v6
	v_mov_b32_e32 v114, v6
	v_mov_b32_e32 v115, v6
	v_mov_b32_e32 v116, v6
	v_mov_b32_e32 v117, v6
	v_mov_b32_e32 v90, v6
	v_mov_b32_e32 v91, v6
	v_mov_b32_e32 v92, v6
	v_mov_b32_e32 v93, v6
	v_mov_b32_e32 v98, v6
	v_mov_b32_e32 v99, v6
	v_mov_b32_e32 v100, v6
	v_mov_b32_e32 v101, v6
	v_mov_b32_e32 v106, v6
	v_mov_b32_e32 v107, v6
	v_mov_b32_e32 v108, v6
	v_mov_b32_e32 v109, v6
	v_mov_b32_e32 v110, v6
	v_mov_b32_e32 v111, v6
	v_mov_b32_e32 v112, v6
	v_mov_b32_e32 v113, v6
	v_mov_b32_e32 v118, v6
	v_mov_b32_e32 v119, v6
	v_mov_b32_e32 v120, v6
	v_mov_b32_e32 v121, v6
	v_mov_b32_e32 v122, v6
	v_mov_b32_e32 v123, v6
	v_mov_b32_e32 v124, v6
	v_mov_b32_e32 v125, v6
	v_mov_b32_e32 v126, v6
	v_mov_b32_e32 v127, v6
	v_mov_b32_e32 v128, v6
	v_mov_b32_e32 v129, v6
	v_mov_b32_e32 v130, v6
	v_mov_b32_e32 v131, v6
	v_mov_b32_e32 v132, v6
	v_mov_b32_e32 v133, v6
	s_barrier
	s_branch .LBB0_270
	s_nop 0
	s_nop 0
	s_nop 0
	s_nop 0
	s_nop 0
	s_nop 0
	s_nop 0
	s_nop 0
	s_nop 0
	s_nop 0
	s_nop 0
	s_nop 0
	s_nop 0
	s_nop 0
	s_nop 0
	s_nop 0
